# odd two-m-tile workgroups pack the next layer's weights before their UP GEMM (HBM work and L2 streaming interleaved across workgroups)
# speedup vs baseline: 1.0107x; 1.0036x over previous
; #define LAS __attribute__((address_space(3)))
; __global__ void __launch_bounds__(NTHR) mega(Params p) {
;     cg::grid_group grid = cg::this_grid();
;     __shared__ __attribute__((aligned(16))) unsigned char lds[LDS_BYTES];
;     __shared__ uint4 xb_words;
;     if (threadIdx.x == 0) xb_words = make_uint4(0u, 0u, 0u, 0u);
;     __syncthreads();
;     (void)xcd_barrier_post((unsigned*)(p.ws + OFF_BAR), (volatile LAS unsigned*)&xb_words);
_Z4mega6Params:
	s_mov_b32 s100, 0
	s_nop 1
	v_writelane_b32 v255, s100, 57
	s_load_dwordx8 s[4:11], s[0:1], 0xe0
	s_load_dwordx8 s[68:75], s[0:1], 0xc0
	s_load_dword s3, s[0:1], 0x100
	s_add_u32 s22, s0, 0xf8
	s_addc_u32 s23, s1, 0
	v_and_b32_e32 v176, 0x3ff, v0
	s_waitcnt lgkmcnt(0)
	v_writelane_b32 v252, s4, 0
	s_nop 1
	v_writelane_b32 v252, s5, 1
	v_writelane_b32 v252, s6, 2
	v_writelane_b32 v252, s7, 3
	v_writelane_b32 v252, s8, 4
	v_writelane_b32 v252, s9, 5
	v_writelane_b32 v252, s10, 6
	v_writelane_b32 v252, s11, 7
	v_cmp_eq_u32_e64 s[6:7], 0, v176
	s_mov_b64 s[4:5], exec
	s_nop 0
	v_writelane_b32 v252, s6, 8
	s_nop 1
	v_writelane_b32 v252, s7, 9
	s_and_b64 s[6:7], s[4:5], s[6:7]
	s_mov_b64 exec, s[6:7]
	s_cbranch_execz .LBB0_2
	v_mov_b32_e32 v2, 0
	v_mov_b32_e32 v3, v2
	v_mov_b32_e32 v4, v2
	v_mov_b32_e32 v5, v2
	v_mov_b32_e32 v1, 0x20400
	ds_write_b128 v1, v[2:5]

; DI int otid() { int t = threadIdx.x; asm volatile("" : "+v"(t)); return t; }
; template <int MODE, int MT> DI void norm_rows(const float* src, const float* src2, float* x, int d2, bf16_t* xb, const float* __restrict__ g) {
;     const int tid_ = otid(), wave = tid_ >> 6, lane = tid_ & 63;
;     for (int rb = 0; rb < MT; ++rb) {
;         f32x4 v[4][4]; float ss[4];
; #pragma unroll
;         for (int q = 0; q < 4; ++q) {
;             const int row = wave * (MT * 4) + rb * 4 + q, grow = row + (row >= 64 ? d2 : 0);
;             const float* s = x + (size_t)grow * DM;
;             if (MODE == 0) { s = src + (size_t)row * DM; if (MT == 3 && row >= 64) s = src2 + (size_t)(row - 64) * DM; }
;             ss[q] = 0.f;
; #pragma unroll
;             for (int i = 0; i < 4; ++i) { v[q][i] = *(const f32x4*)(s + i * 256 + lane * 4); ss[q] += v[q][i][0] * v[q][i][0] + v[q][i][1] * v[q][i][1] + v[q][i][2] * v[q][i][2] + v[q][i][3] * v[q][i][3]; }
;         }
; #pragma unroll
;         for (int o = 32; o >= 1; o >>= 1)
; #pragma unroll
;             for (int q = 0; q < 4; ++q) ss[q] += __shfl_xor(ss[q], o);
.LBB0_537:
	v_mov_b32_e32 v2, v176
	s_barrier
	v_mov_b32_e32 v3, v1
	v_ashrrev_i32_e32 v0, 3, v2
	v_lshlrev_b32_e32 v2, 2, v2
	v_and_b32_e32 v72, -8, v0
	v_and_b32_e32 v30, 0xfc, v2
	v_lshlrev_b32_e32 v2, 2, v30
	v_ashrrev_i32_e32 v73, 31, v72
	v_lshl_add_u64 v[68:69], s[0:1], 0, v[2:3]
	v_lshlrev_b64 v[2:3], 12, v[72:73]
	v_or_b32_e32 v76, 1, v72
	v_lshl_add_u64 v[2:3], v[68:69], 0, v[2:3]
	v_ashrrev_i32_e32 v77, 31, v76
	global_load_dwordx4 v[54:57], v[2:3], off
	global_load_dwordx4 v[50:53], v[2:3], off offset:1024
	global_load_dwordx4 v[62:65], v[2:3], off offset:2048
	global_load_dwordx4 v[58:61], v[2:3], off offset:3072
	v_lshlrev_b64 v[2:3], 12, v[76:77]
	v_lshl_add_u64 v[6:7], v[68:69], 0, v[2:3]
	global_load_dwordx4 v[26:29], v[6:7], off
	global_load_dwordx4 v[2:5], v[6:7], off offset:1024
	global_load_dwordx4 v[22:25], v[6:7], off offset:2048
	s_nop 0
	global_load_dwordx4 v[6:9], v[6:7], off offset:3072
	v_or_b32_e32 v74, 2, v72
	v_ashrrev_i32_e32 v75, 31, v74
	v_lshlrev_b64 v[10:11], 12, v[74:75]
	v_lshl_add_u64 v[10:11], v[68:69], 0, v[10:11]
	global_load_dwordx4 v[18:21], v[10:11], off
	global_load_dwordx4 v[14:17], v[10:11], off offset:1024
	global_load_dwordx4 v[34:37], v[10:11], off offset:2048
	s_nop 0
	global_load_dwordx4 v[10:13], v[10:11], off offset:3072
	v_or_b32_e32 v78, 3, v72
	v_mov_b32_e32 v31, v1
	v_lshlrev_b32_e32 v30, 1, v30
	v_ashrrev_i32_e32 v79, 31, v78
	v_lshl_add_u64 v[66:67], s[4:5], 0, v[30:31]
	v_lshlrev_b64 v[30:31], 12, v[78:79]
	v_lshl_add_u64 v[42:43], v[68:69], 0, v[30:31]
	global_load_dwordx4 v[38:41], v[42:43], off
	global_load_dwordx4 v[30:33], v[42:43], off offset:1024
	global_load_dwordx4 v[46:49], v[42:43], off offset:2048
	s_nop 0
	global_load_dwordx4 v[42:45], v[42:43], off offset:3072
	s_mov_b32 s0, 0x358637bd
	s_mov_b32 s2, 0x3a800000
	s_waitcnt vmcnt(15)
	v_mov_b32_e32 v80, v55
	s_waitcnt vmcnt(14)
	v_mov_b32_e32 v81, v51
	s_waitcnt vmcnt(13)
	v_mov_b32_e32 v88, v63
	s_waitcnt vmcnt(12)
	v_mov_b32_e32 v89, v59
	v_mov_b32_e32 v70, v54
	v_mov_b32_e32 v71, v50
	v_mov_b32_e32 v86, v62
	v_mov_b32_e32 v87, v58
	v_pk_mul_f32 v[80:81], v[80:81], v[80:81]
	v_pk_mul_f32 v[88:89], v[88:89], v[88:89]
	s_waitcnt vmcnt(11)
	v_mov_b32_e32 v96, v27
	s_waitcnt vmcnt(10)
	v_mov_b32_e32 v97, v3
	v_mov_b32_e32 v82, v56
	v_mov_b32_e32 v83, v52
	v_mov_b32_e32 v94, v26
	v_mov_b32_e32 v95, v2
	s_waitcnt vmcnt(9)
	v_mov_b32_e32 v104, v23
	s_waitcnt vmcnt(8)
	v_mov_b32_e32 v105, v7
	v_pk_fma_f32 v[70:71], v[70:71], v[70:71], v[80:81]
	v_pk_fma_f32 v[80:81], v[86:87], v[86:87], v[88:89]
	v_pk_mul_f32 v[86:87], v[96:97], v[96:97]
	v_mov_b32_e32 v98, v28
	v_mov_b32_e32 v99, v4
	v_mov_b32_e32 v102, v22
	v_mov_b32_e32 v103, v6
	v_pk_mul_f32 v[88:89], v[104:105], v[104:105]
	v_pk_fma_f32 v[70:71], v[82:83], v[82:83], v[70:71]
	v_pk_fma_f32 v[82:83], v[94:95], v[94:95], v[86:87]
	v_mov_b32_e32 v84, v57
	v_mov_b32_e32 v85, v53
	v_mov_b32_e32 v90, v64
	v_mov_b32_e32 v91, v60
	v_mov_b32_e32 v100, v29
	v_mov_b32_e32 v101, v5
	v_mov_b32_e32 v106, v24
	v_mov_b32_e32 v107, v8
	v_pk_fma_f32 v[86:87], v[102:103], v[102:103], v[88:89]
	v_pk_fma_f32 v[82:83], v[98:99], v[98:99], v[82:83]
	v_mov_b32_e32 v92, v65
	v_mov_b32_e32 v93, v61
	v_mov_b32_e32 v108, v25
	v_mov_b32_e32 v109, v9
	v_pk_fma_f32 v[80:81], v[90:91], v[90:91], v[80:81]
	v_pk_fma_f32 v[70:71], v[84:85], v[84:85], v[70:71]
	v_pk_fma_f32 v[84:85], v[106:107], v[106:107], v[86:87]
	v_pk_fma_f32 v[82:83], v[100:101], v[100:101], v[82:83]
	v_pk_fma_f32 v[80:81], v[92:93], v[92:93], v[80:81]
	v_pk_fma_f32 v[84:85], v[108:109], v[108:109], v[84:85]
	v_mov_b32_e32 v92, v82
	v_mov_b32_e32 v93, v70
	v_mov_b32_e32 v70, v83
	v_pk_add_f32 v[70:71], v[92:93], v[70:71]
	v_mov_b32_e32 v82, v84
	v_mov_b32_e32 v83, v80
	v_pk_add_f32 v[70:71], v[70:71], v[82:83]
	v_mov_b32_e32 v80, v85
	v_pk_add_f32 v[70:71], v[70:71], v[80:81]
	ds_bpermute_b32 v81, v163, v71
	ds_bpermute_b32 v80, v163, v70
	s_waitcnt vmcnt(7)
	v_mov_b32_e32 v88, v19
	s_waitcnt vmcnt(6)
	v_mov_b32_e32 v89, v15
	v_mov_b32_e32 v86, v18
	v_mov_b32_e32 v87, v14
	s_waitcnt lgkmcnt(0)
	v_pk_add_f32 v[70:71], v[70:71], v[80:81]
	ds_bpermute_b32 v81, v164, v71
	ds_bpermute_b32 v80, v164, v70
	v_pk_mul_f32 v[88:89], v[88:89], v[88:89]
	s_waitcnt vmcnt(5)
	v_mov_b32_e32 v90, v35
	v_pk_fma_f32 v[86:87], v[86:87], v[86:87], v[88:89]
	v_mov_b32_e32 v88, v20
	s_waitcnt lgkmcnt(0)
	v_pk_add_f32 v[70:71], v[70:71], v[80:81]
	ds_bpermute_b32 v81, v165, v71
	ds_bpermute_b32 v80, v165, v70
	v_mov_b32_e32 v89, v16
	v_pk_fma_f32 v[86:87], v[88:89], v[88:89], v[86:87]
	v_mov_b32_e32 v88, v21
	v_mov_b32_e32 v89, v17
	s_waitcnt lgkmcnt(0)
	v_pk_add_f32 v[70:71], v[70:71], v[80:81]
	ds_bpermute_b32 v81, v166, v71
	ds_bpermute_b32 v80, v166, v70
	s_waitcnt vmcnt(4)
	v_mov_b32_e32 v91, v11
	v_pk_fma_f32 v[86:87], v[88:89], v[88:89], v[86:87]
	v_mov_b32_e32 v88, v34
	v_mov_b32_e32 v89, v10
	s_waitcnt lgkmcnt(0)
	v_pk_add_f32 v[70:71], v[70:71], v[80:81]
	ds_bpermute_b32 v81, v167, v71
	ds_bpermute_b32 v80, v167, v70
	v_pk_mul_f32 v[90:91], v[90:91], v[90:91]
	s_waitcnt vmcnt(3)
	v_mov_b32_e32 v84, v38
	v_pk_fma_f32 v[88:89], v[88:89], v[88:89], v[90:91]
	v_mov_b32_e32 v90, v36
	s_waitcnt lgkmcnt(0)
	v_pk_add_f32 v[70:71], v[70:71], v[80:81]
	ds_bpermute_b32 v81, v168, v71
	ds_bpermute_b32 v80, v168, v70
	v_mov_b32_e32 v91, v12
	v_pk_fma_f32 v[88:89], v[90:91], v[90:91], v[88:89]
	v_mov_b32_e32 v90, v37
	v_mov_b32_e32 v91, v13
	s_waitcnt lgkmcnt(0)
	v_pk_add_f32 v[80:81], v[70:71], v[80:81]
	v_mov_b64_e32 v[70:71], s[0:1]
	v_pk_fma_f32 v[82:83], v[90:91], v[90:91], v[88:89]
	v_mov_b32_e32 v88, v39
	s_waitcnt vmcnt(2)
; DI unsigned pk2(float lo, float hi) { f32x2 v = {lo, hi}; bf2_t b = __builtin_convertvector(v, bf2_t); return __builtin_bit_cast(unsigned, b); }
; template <int MODE, int MT> DI void norm_rows(const float* src, const float* src2, float* x, int d2, bf16_t* xb, const float* __restrict__ g) {
;     ...
;             for (int i = 0; i < 4; ++i) { v[q][i] = *(const f32x4*)(s + i * 256 + lane * 4); ss[q] += v[q][i][0] * v[q][i][0] + v[q][i][1] * v[q][i][1] + v[q][i][2] * v[q][i][2] + v[q][i][3] * v[q][i][3]; }
;         }
; #pragma unroll
;         for (int o = 32; o >= 1; o >>= 1)
; #pragma unroll
;             for (int q = 0; q < 4; ++q) ss[q] += __shfl_xor(ss[q], o);
; #pragma unroll
;         for (int q = 0; q < 4; ++q) {
;             const int row = wave * (MT * 4) + rb * 4 + q, grow = row + (row >= 64 ? d2 : 0);
;             const float rstd = rsqrtf(ss[q] * (1.f / DM) + 1e-6f);
; #pragma unroll
;             for (int i = 0; i < 4; ++i) {
;                 if (MODE == 0) *(f32x4*)(x + (size_t)grow * DM + i * 256 + lane * 4) = v[q][i];
;                 if (MODE == 2) { f32x4 gg = *(const f32x4*)(g + i * 256 + lane * 4); *(f32x4*)(x + (size_t)grow * DM + i * 256 + lane * 4) = v[q][i] * rstd * gg; }
;                 else { u32x2 o = {pk2(v[q][i][0] * rstd, v[q][i][1] * rstd), pk2(v[q][i][2] * rstd, v[q][i][3] * rstd)}; *(u32x2*)(xb + (size_t)grow * DM + i * 256 + lane * 4) = o; }
	v_mov_b32_e32 v89, v31
	v_pk_fma_f32 v[80:81], v[80:81], s[2:3], v[70:71] op_sel_hi:[1,0,0]
	s_mov_b32 s0, 0x800000
	v_mov_b32_e32 v85, v30
	v_pk_mul_f32 v[88:89], v[88:89], v[88:89]
	v_mul_f32_e32 v92, 0x4b800000, v81
	v_cmp_gt_f32_e32 vcc, s0, v81
	v_pk_fma_f32 v[84:85], v[84:85], v[84:85], v[88:89]
	v_mov_b32_e32 v88, v40
	v_mov_b32_e32 v89, v32
	v_cndmask_b32_e32 v81, v81, v92, vcc
	v_pk_fma_f32 v[84:85], v[88:89], v[88:89], v[84:85]
	v_mov_b32_e32 v88, v41
	v_mov_b32_e32 v89, v33
	s_waitcnt vmcnt(1)
	v_mov_b32_e32 v90, v47
	s_waitcnt vmcnt(0)
	v_mov_b32_e32 v91, v43
	v_rsq_f32_e32 v81, v81
	v_pk_fma_f32 v[84:85], v[88:89], v[88:89], v[84:85]
	v_mov_b32_e32 v88, v46
	v_mov_b32_e32 v89, v42
	v_pk_mul_f32 v[90:91], v[90:91], v[90:91]
	s_nop 0
	v_pk_fma_f32 v[88:89], v[88:89], v[88:89], v[90:91]
	v_mov_b32_e32 v90, v48
	v_mov_b32_e32 v91, v44
	v_pk_fma_f32 v[88:89], v[90:91], v[90:91], v[88:89]
	v_mov_b32_e32 v90, v49
	v_mov_b32_e32 v91, v45
	v_pk_fma_f32 v[88:89], v[90:91], v[90:91], v[88:89]
	v_lshlrev_b64 v[90:91], 11, v[72:73]
	v_mul_f32_e32 v73, 0x45800000, v81
	v_cndmask_b32_e32 v92, v81, v73, vcc
	v_pk_mul_f32 v[50:51], v[50:51], v[92:93] op_sel_hi:[1,0]
	v_pk_mul_f32 v[52:53], v[52:53], v[92:93] op_sel_hi:[1,0]
	v_lshl_add_u64 v[90:91], v[66:67], 0, v[90:91]
	v_cvt_pk_f16_f32 v50, v50, v51
	v_cvt_pk_f16_f32 v51, v52, v53
	global_store_dwordx2 v[90:91], v[50:51], off offset:512
	v_pk_mul_f32 v[50:51], v[62:63], v[92:93] op_sel_hi:[1,0]
	v_pk_mul_f32 v[52:53], v[64:65], v[92:93] op_sel_hi:[1,0]
	v_cvt_pk_f16_f32 v50, v50, v51
	v_cvt_pk_f16_f32 v51, v52, v53
	global_store_dwordx2 v[90:91], v[50:51], off offset:1024
	v_pk_mul_f32 v[50:51], v[58:59], v[92:93] op_sel_hi:[1,0]
	v_pk_mul_f32 v[52:53], v[60:61], v[92:93] op_sel_hi:[1,0]
	v_cvt_pk_f16_f32 v50, v50, v51
	v_cvt_pk_f16_f32 v51, v52, v53
	v_mul_f32_e32 v52, 0x4b800000, v80
	v_cmp_gt_f32_e32 vcc, s0, v80
	v_pk_mul_f32 v[54:55], v[54:55], v[92:93] op_sel_hi:[1,0]
	v_pk_mul_f32 v[56:57], v[56:57], v[92:93] op_sel_hi:[1,0]
	v_cndmask_b32_e32 v52, v80, v52, vcc
	v_cvt_pk_f16_f32 v54, v54, v55
	v_cvt_pk_f16_f32 v55, v56, v57
	v_rsq_f32_e32 v56, v52
	v_mov_b32_e32 v52, v84
	v_mov_b32_e32 v53, v86
	v_mov_b32_e32 v86, v85
	global_store_dwordx2 v[90:91], v[54:55], off
	v_pk_add_f32 v[52:53], v[52:53], v[86:87]
	v_mov_b32_e32 v54, v88
	v_mov_b32_e32 v55, v82
	v_pk_add_f32 v[52:53], v[52:53], v[54:55]
	v_mov_b32_e32 v82, v89
	v_pk_add_f32 v[52:53], v[52:53], v[82:83]
	ds_bpermute_b32 v55, v163, v53
	ds_bpermute_b32 v54, v163, v52
	global_store_dwordx2 v[90:91], v[50:51], off offset:1536
	v_mul_f32_e32 v50, 0x45800000, v56
	v_cndmask_b32_e32 v50, v56, v50, vcc
	v_lshlrev_b64 v[56:57], 11, v[76:77]
	s_waitcnt lgkmcnt(0)
	v_pk_add_f32 v[52:53], v[52:53], v[54:55]
	ds_bpermute_b32 v55, v164, v53
	ds_bpermute_b32 v54, v164, v52
	v_pk_mul_f32 v[26:27], v[26:27], v[50:51] op_sel_hi:[1,0]
	v_pk_mul_f32 v[28:29], v[28:29], v[50:51] op_sel_hi:[1,0]
	v_lshl_add_u64 v[56:57], v[66:67], 0, v[56:57]
	v_cvt_pk_f16_f32 v26, v26, v27
	s_waitcnt lgkmcnt(0)
	v_pk_add_f32 v[52:53], v[52:53], v[54:55]
	ds_bpermute_b32 v55, v165, v53
	ds_bpermute_b32 v54, v165, v52
	v_cvt_pk_f16_f32 v27, v28, v29
	global_store_dwordx2 v[56:57], v[26:27], off
	v_pk_mul_f32 v[2:3], v[2:3], v[50:51] op_sel_hi:[1,0]
	v_pk_mul_f32 v[4:5], v[4:5], v[50:51] op_sel_hi:[1,0]
	s_waitcnt lgkmcnt(0)
	v_pk_add_f32 v[26:27], v[52:53], v[54:55]
	ds_bpermute_b32 v29, v166, v27
	ds_bpermute_b32 v28, v166, v26
	v_cvt_pk_f16_f32 v2, v2, v3
	v_cvt_pk_f16_f32 v3, v4, v5
	global_store_dwordx2 v[56:57], v[2:3], off offset:512
	v_pk_mul_f32 v[2:3], v[22:23], v[50:51] op_sel_hi:[1,0]
	s_waitcnt lgkmcnt(0)
	v_pk_add_f32 v[4:5], v[26:27], v[28:29]
	ds_bpermute_b32 v23, v167, v5
	ds_bpermute_b32 v22, v167, v4
	v_pk_mul_f32 v[24:25], v[24:25], v[50:51] op_sel_hi:[1,0]
	v_cvt_pk_f16_f32 v2, v2, v3
	v_cvt_pk_f16_f32 v3, v24, v25
	global_store_dwordx2 v[56:57], v[2:3], off offset:1024
	s_waitcnt lgkmcnt(0)
	v_pk_add_f32 v[2:3], v[4:5], v[22:23]
	ds_bpermute_b32 v5, v168, v3
	ds_bpermute_b32 v4, v168, v2
	v_pk_mul_f32 v[6:7], v[6:7], v[50:51] op_sel_hi:[1,0]
	v_pk_mul_f32 v[8:9], v[8:9], v[50:51] op_sel_hi:[1,0]
	v_cvt_pk_f16_f32 v6, v6, v7
	v_cvt_pk_f16_f32 v7, v8, v9
	s_waitcnt lgkmcnt(0)
; DI unsigned pk2(float lo, float hi) { f32x2 v = {lo, hi}; bf2_t b = __builtin_convertvector(v, bf2_t); return __builtin_bit_cast(unsigned, b); }
; template <int MODE, int MT> DI void norm_rows(const float* src, const float* src2, float* x, int d2, bf16_t* xb, const float* __restrict__ g) {
;     ...
; #pragma unroll
;         for (int q = 0; q < 4; ++q) {
;             const int row = wave * (MT * 4) + rb * 4 + q, grow = row + (row >= 64 ? d2 : 0);
;             const float rstd = rsqrtf(ss[q] * (1.f / DM) + 1e-6f);
; #pragma unroll
;             for (int i = 0; i < 4; ++i) {
;                 if (MODE == 0) *(f32x4*)(x + (size_t)grow * DM + i * 256 + lane * 4) = v[q][i];
;                 if (MODE == 2) { f32x4 gg = *(const f32x4*)(g + i * 256 + lane * 4); *(f32x4*)(x + (size_t)grow * DM + i * 256 + lane * 4) = v[q][i] * rstd * gg; }
;                 else { u32x2 o = {pk2(v[q][i][0] * rstd, v[q][i][1] * rstd), pk2(v[q][i][2] * rstd, v[q][i][3] * rstd)}; *(u32x2*)(xb + (size_t)grow * DM + i * 256 + lane * 4) = o; }
;             }
;         }
	v_pk_add_f32 v[2:3], v[2:3], v[4:5]
	global_store_dwordx2 v[56:57], v[6:7], off offset:1536
	v_pk_fma_f32 v[2:3], v[2:3], s[2:3], v[70:71] op_sel_hi:[1,0,0]
	v_or_b32_e32 v76, 7, v0
	v_mul_f32_e32 v4, 0x4b800000, v3
	v_cmp_gt_f32_e32 vcc, s0, v3
	v_ashrrev_i32_e32 v77, 31, v76
	s_nop 0
	v_cndmask_b32_e32 v3, v3, v4, vcc
	v_rsq_f32_e32 v3, v3
	v_lshlrev_b64 v[4:5], 11, v[74:75]
	v_lshl_add_u64 v[4:5], v[66:67], 0, v[4:5]
	v_or_b32_e32 v74, 5, v72
	v_mul_f32_e32 v6, 0x45800000, v3
	v_cndmask_b32_e32 v6, v3, v6, vcc
	v_pk_mul_f32 v[8:9], v[18:19], v[6:7] op_sel_hi:[1,0]
	v_pk_mul_f32 v[18:19], v[20:21], v[6:7] op_sel_hi:[1,0]
	v_cvt_pk_f16_f32 v8, v8, v9
	v_cvt_pk_f16_f32 v9, v18, v19
	global_store_dwordx2 v[4:5], v[8:9], off
	v_pk_mul_f32 v[8:9], v[14:15], v[6:7] op_sel_hi:[1,0]
	v_pk_mul_f32 v[14:15], v[16:17], v[6:7] op_sel_hi:[1,0]
	v_cvt_pk_f16_f32 v8, v8, v9
	v_cvt_pk_f16_f32 v9, v14, v15
	global_store_dwordx2 v[4:5], v[8:9], off offset:512
	v_pk_mul_f32 v[8:9], v[34:35], v[6:7] op_sel_hi:[1,0]
	v_pk_mul_f32 v[14:15], v[36:37], v[6:7] op_sel_hi:[1,0]
	v_mul_f32_e32 v3, 0x4b800000, v2
	v_cmp_gt_f32_e32 vcc, s0, v2
	v_cvt_pk_f16_f32 v8, v8, v9
	v_cvt_pk_f16_f32 v9, v14, v15
	v_cndmask_b32_e32 v2, v2, v3, vcc
	global_store_dwordx2 v[4:5], v[8:9], off offset:1024
	v_pk_mul_f32 v[8:9], v[10:11], v[6:7] op_sel_hi:[1,0]
	v_rsq_f32_e32 v7, v2
	v_cvt_pk_f16_f32 v8, v8, v9
	v_ashrrev_i32_e32 v75, 31, v74
	v_pk_mul_f32 v[2:3], v[12:13], v[6:7] op_sel_hi:[1,0]
	s_nop 0
	v_cvt_pk_f16_f32 v9, v2, v3
	v_mul_f32_e32 v2, 0x45800000, v7
	v_cndmask_b32_e32 v2, v7, v2, vcc
	global_store_dwordx2 v[4:5], v[8:9], off offset:1536
	v_lshlrev_b64 v[4:5], 11, v[78:79]
	v_pk_mul_f32 v[6:7], v[38:39], v[2:3] op_sel_hi:[1,0]
	v_pk_mul_f32 v[8:9], v[40:41], v[2:3] op_sel_hi:[1,0]
	v_lshl_add_u64 v[4:5], v[66:67], 0, v[4:5]
	v_cvt_pk_f16_f32 v6, v6, v7
	v_cvt_pk_f16_f32 v7, v8, v9
	global_store_dwordx2 v[4:5], v[6:7], off
	v_pk_mul_f32 v[6:7], v[30:31], v[2:3] op_sel_hi:[1,0]
	v_pk_mul_f32 v[8:9], v[32:33], v[2:3] op_sel_hi:[1,0]
	v_cvt_pk_f16_f32 v6, v6, v7
	v_cvt_pk_f16_f32 v7, v8, v9
	global_store_dwordx2 v[4:5], v[6:7], off offset:512
	v_pk_mul_f32 v[6:7], v[46:47], v[2:3] op_sel_hi:[1,0]
	v_pk_mul_f32 v[8:9], v[48:49], v[2:3] op_sel_hi:[1,0]
	v_cvt_pk_f16_f32 v6, v6, v7
	v_cvt_pk_f16_f32 v7, v8, v9
	v_or_b32_e32 v78, 4, v72
	global_store_dwordx2 v[4:5], v[6:7], off offset:1024
	v_pk_mul_f32 v[6:7], v[42:43], v[2:3] op_sel_hi:[1,0]
	v_pk_mul_f32 v[2:3], v[44:45], v[2:3] op_sel_hi:[1,0]
	v_ashrrev_i32_e32 v79, 31, v78
	v_cvt_pk_f16_f32 v6, v6, v7
	v_cvt_pk_f16_f32 v7, v2, v3
	v_lshlrev_b64 v[2:3], 12, v[78:79]
	global_store_dwordx2 v[4:5], v[6:7], off offset:1536
	v_lshl_add_u64 v[2:3], v[68:69], 0, v[2:3]
	global_load_dwordx4 v[54:57], v[2:3], off
	global_load_dwordx4 v[46:49], v[2:3], off offset:1024
	global_load_dwordx4 v[62:65], v[2:3], off offset:2048
	global_load_dwordx4 v[58:61], v[2:3], off offset:3072
	v_lshlrev_b64 v[2:3], 12, v[74:75]
	v_lshl_add_u64 v[6:7], v[68:69], 0, v[2:3]
	global_load_dwordx4 v[26:29], v[6:7], off
	global_load_dwordx4 v[2:5], v[6:7], off offset:1024
	global_load_dwordx4 v[22:25], v[6:7], off offset:2048
	global_load_dwordx4 v[10:13], v[6:7], off offset:3072
	v_or_b32_e32 v72, 6, v72
	v_ashrrev_i32_e32 v73, 31, v72
	v_lshlrev_b64 v[6:7], 12, v[72:73]
	v_lshl_add_u64 v[6:7], v[68:69], 0, v[6:7]
	global_load_dwordx4 v[18:21], v[6:7], off
	global_load_dwordx4 v[14:17], v[6:7], off offset:1024
	global_load_dwordx4 v[30:33], v[6:7], off offset:2048
	s_nop 0
	global_load_dwordx4 v[6:9], v[6:7], off offset:3072
	v_lshlrev_b64 v[78:79], 11, v[78:79]
	v_lshl_add_u64 v[78:79], v[66:67], 0, v[78:79]
	s_waitcnt vmcnt(11)
	v_mov_b32_e32 v36, v55
	s_waitcnt vmcnt(10)
	v_mov_b32_e32 v37, v47
	v_mov_b32_e32 v34, v54
	v_mov_b32_e32 v35, v46
	v_pk_mul_f32 v[36:37], v[36:37], v[36:37]
	v_mov_b32_e32 v44, v56
	v_pk_fma_f32 v[42:43], v[34:35], v[34:35], v[36:37]
	v_mov_b32_e32 v45, v48
	v_lshlrev_b64 v[34:35], 12, v[76:77]
	v_pk_fma_f32 v[42:43], v[44:45], v[44:45], v[42:43]
	v_mov_b32_e32 v44, v57
	v_mov_b32_e32 v45, v49
	v_lshl_add_u64 v[68:69], v[68:69], 0, v[34:35]
	v_pk_fma_f32 v[80:81], v[44:45], v[44:45], v[42:43]
	s_waitcnt vmcnt(9)
	v_mov_b32_e32 v44, v63
	s_waitcnt vmcnt(8)
	v_mov_b32_e32 v45, v59
	global_load_dwordx4 v[38:41], v[68:69], off
	global_load_dwordx4 v[34:37], v[68:69], off offset:1024
	v_mov_b32_e32 v42, v62
	v_mov_b32_e32 v43, v58
	v_pk_mul_f32 v[44:45], v[44:45], v[44:45]
	s_waitcnt vmcnt(9)
	v_mov_b32_e32 v84, v26
	v_pk_fma_f32 v[42:43], v[42:43], v[42:43], v[44:45]
	v_mov_b32_e32 v44, v64
	v_mov_b32_e32 v45, v60
	v_pk_fma_f32 v[42:43], v[44:45], v[44:45], v[42:43]
	v_mov_b32_e32 v44, v65
	v_mov_b32_e32 v45, v61
	v_pk_fma_f32 v[82:83], v[44:45], v[44:45], v[42:43]
	global_load_dwordx4 v[50:53], v[68:69], off offset:2048
	global_load_dwordx4 v[42:45], v[68:69], off offset:3072
	v_mov_b32_e32 v68, v27
	s_waitcnt vmcnt(10)
	v_mov_b32_e32 v69, v3
	v_mov_b32_e32 v85, v2
	v_pk_mul_f32 v[68:69], v[68:69], v[68:69]
	s_waitcnt vmcnt(9)
	v_mov_b32_e32 v86, v23
	v_pk_fma_f32 v[68:69], v[84:85], v[84:85], v[68:69]
	v_mov_b32_e32 v84, v28
	v_mov_b32_e32 v85, v4
	v_pk_fma_f32 v[68:69], v[84:85], v[84:85], v[68:69]
	v_mov_b32_e32 v84, v29
	v_mov_b32_e32 v85, v5
	s_waitcnt vmcnt(8)
; DI unsigned pk2(float lo, float hi) { f32x2 v = {lo, hi}; bf2_t b = __builtin_convertvector(v, bf2_t); return __builtin_bit_cast(unsigned, b); }
; template <int MODE, int MT> DI void norm_rows(const float* src, const float* src2, float* x, int d2, bf16_t* xb, const float* __restrict__ g) {
;     ...
;     for (int rb = 0; rb < MT; ++rb) {
;         f32x4 v[4][4]; float ss[4];
; #pragma unroll
;         for (int q = 0; q < 4; ++q) {
;             const int row = wave * (MT * 4) + rb * 4 + q, grow = row + (row >= 64 ? d2 : 0);
;             const float* s = x + (size_t)grow * DM;
;             if (MODE == 0) { s = src + (size_t)row * DM; if (MT == 3 && row >= 64) s = src2 + (size_t)(row - 64) * DM; }
;             ss[q] = 0.f;
; #pragma unroll
;             for (int i = 0; i < 4; ++i) { v[q][i] = *(const f32x4*)(s + i * 256 + lane * 4); ss[q] += v[q][i][0] * v[q][i][0] + v[q][i][1] * v[q][i][1] + v[q][i][2] * v[q][i][2] + v[q][i][3] * v[q][i][3]; }
;         }
; #pragma unroll
;         for (int o = 32; o >= 1; o >>= 1)
; #pragma unroll
;             for (int q = 0; q < 4; ++q) ss[q] += __shfl_xor(ss[q], o);
; #pragma unroll
;         for (int q = 0; q < 4; ++q) {
;             const int row = wave * (MT * 4) + rb * 4 + q, grow = row + (row >= 64 ? d2 : 0);
;             const float rstd = rsqrtf(ss[q] * (1.f / DM) + 1e-6f);
; #pragma unroll
;             for (int i = 0; i < 4; ++i) {
;                 if (MODE == 0) *(f32x4*)(x + (size_t)grow * DM + i * 256 + lane * 4) = v[q][i];
;                 if (MODE == 2) { f32x4 gg = *(const f32x4*)(g + i * 256 + lane * 4); *(f32x4*)(x + (size_t)grow * DM + i * 256 + lane * 4) = v[q][i] * rstd * gg; }
;                 else { u32x2 o = {pk2(v[q][i][0] * rstd, v[q][i][1] * rstd), pk2(v[q][i][2] * rstd, v[q][i][3] * rstd)}; *(u32x2*)(xb + (size_t)grow * DM + i * 256 + lane * 4) = o; }
	v_mov_b32_e32 v87, v11
	v_pk_fma_f32 v[68:69], v[84:85], v[84:85], v[68:69]
	v_mov_b32_e32 v84, v22
	v_mov_b32_e32 v85, v10
	v_pk_mul_f32 v[86:87], v[86:87], v[86:87]
	v_mov_b32_e32 v92, v68
	v_pk_fma_f32 v[84:85], v[84:85], v[84:85], v[86:87]
	v_mov_b32_e32 v86, v24
	v_mov_b32_e32 v87, v12
	v_pk_fma_f32 v[84:85], v[86:87], v[86:87], v[84:85]
	v_mov_b32_e32 v86, v25
	v_mov_b32_e32 v87, v13
	v_pk_fma_f32 v[84:85], v[86:87], v[86:87], v[84:85]
	v_mov_b32_e32 v93, v80
	v_mov_b32_e32 v80, v69
	v_pk_add_f32 v[68:69], v[92:93], v[80:81]
	v_mov_b32_e32 v80, v84
	v_mov_b32_e32 v81, v82
	v_pk_add_f32 v[68:69], v[68:69], v[80:81]
	v_mov_b32_e32 v82, v85
	v_pk_add_f32 v[68:69], v[68:69], v[82:83]
	ds_bpermute_b32 v81, v163, v69
	ds_bpermute_b32 v80, v163, v68
	s_waitcnt vmcnt(7)
	v_mov_b32_e32 v88, v19
	s_waitcnt vmcnt(6)
	v_mov_b32_e32 v89, v15
	v_mov_b32_e32 v86, v18
	v_mov_b32_e32 v87, v14
	s_waitcnt lgkmcnt(0)
	v_pk_add_f32 v[68:69], v[68:69], v[80:81]
	ds_bpermute_b32 v81, v164, v69
	ds_bpermute_b32 v80, v164, v68
	v_pk_mul_f32 v[88:89], v[88:89], v[88:89]
	s_waitcnt vmcnt(5)
	v_mov_b32_e32 v90, v31
	v_pk_fma_f32 v[86:87], v[86:87], v[86:87], v[88:89]
	v_mov_b32_e32 v88, v20
	s_waitcnt lgkmcnt(0)
	v_pk_add_f32 v[68:69], v[68:69], v[80:81]
	ds_bpermute_b32 v81, v165, v69
	ds_bpermute_b32 v80, v165, v68
	v_mov_b32_e32 v89, v16
	v_pk_fma_f32 v[86:87], v[88:89], v[88:89], v[86:87]
	v_mov_b32_e32 v88, v21
	v_mov_b32_e32 v89, v17
	s_waitcnt lgkmcnt(0)
	v_pk_add_f32 v[68:69], v[68:69], v[80:81]
	ds_bpermute_b32 v81, v166, v69
	ds_bpermute_b32 v80, v166, v68
	s_waitcnt vmcnt(4)
	v_mov_b32_e32 v91, v7
	v_pk_fma_f32 v[86:87], v[88:89], v[88:89], v[86:87]
	v_mov_b32_e32 v88, v30
	v_mov_b32_e32 v89, v6
	s_waitcnt lgkmcnt(0)
	v_pk_add_f32 v[68:69], v[68:69], v[80:81]
	ds_bpermute_b32 v81, v167, v69
	ds_bpermute_b32 v80, v167, v68
	v_pk_mul_f32 v[90:91], v[90:91], v[90:91]
	s_waitcnt lgkmcnt(0)
	v_pk_add_f32 v[68:69], v[68:69], v[80:81]
	ds_bpermute_b32 v81, v168, v69
	ds_bpermute_b32 v80, v168, v68
	v_pk_fma_f32 v[88:89], v[88:89], v[88:89], v[90:91]
	v_mov_b32_e32 v90, v32
	v_mov_b32_e32 v91, v8
	v_pk_fma_f32 v[88:89], v[90:91], v[90:91], v[88:89]
	s_waitcnt lgkmcnt(0)
	v_pk_add_f32 v[68:69], v[68:69], v[80:81]
	v_mov_b32_e32 v90, v33
	v_pk_fma_f32 v[68:69], v[68:69], s[2:3], v[70:71] op_sel_hi:[1,0,0]
	v_mov_b32_e32 v91, v9
	v_mul_f32_e32 v0, 0x4b800000, v69
	v_cmp_gt_f32_e32 vcc, s0, v69
	v_pk_fma_f32 v[82:83], v[90:91], v[90:91], v[88:89]
	s_waitcnt vmcnt(3)
	v_mov_b32_e32 v88, v39
	v_cndmask_b32_e32 v0, v69, v0, vcc
	v_rsq_f32_e32 v0, v0
	s_waitcnt vmcnt(2)
	v_mov_b32_e32 v89, v35
	v_mov_b32_e32 v84, v38
	v_mov_b32_e32 v85, v34
	v_mul_f32_e32 v69, 0x45800000, v0
	v_pk_mul_f32 v[88:89], v[88:89], v[88:89]
	v_cndmask_b32_e32 v0, v0, v69, vcc
	v_pk_fma_f32 v[84:85], v[84:85], v[84:85], v[88:89]
	v_mov_b32_e32 v88, v40
	v_mov_b32_e32 v89, v36
	v_pk_mul_f32 v[46:47], v[46:47], v[0:1] op_sel_hi:[1,0]
	v_pk_mul_f32 v[48:49], v[48:49], v[0:1] op_sel_hi:[1,0]
	v_pk_fma_f32 v[84:85], v[88:89], v[88:89], v[84:85]
	v_mov_b32_e32 v88, v41
	v_mov_b32_e32 v89, v37
	s_waitcnt vmcnt(1)
	v_mov_b32_e32 v90, v51
	s_waitcnt vmcnt(0)
	v_mov_b32_e32 v91, v43
	v_cvt_pk_f16_f32 v46, v46, v47
	v_cvt_pk_f16_f32 v47, v48, v49
	v_pk_fma_f32 v[84:85], v[88:89], v[88:89], v[84:85]
	v_mov_b32_e32 v88, v50
	v_mov_b32_e32 v89, v42
	v_pk_mul_f32 v[90:91], v[90:91], v[90:91]
	global_store_dwordx2 v[78:79], v[46:47], off offset:512
	v_pk_mul_f32 v[46:47], v[62:63], v[0:1] op_sel_hi:[1,0]
	v_pk_mul_f32 v[48:49], v[64:65], v[0:1] op_sel_hi:[1,0]
	v_pk_fma_f32 v[88:89], v[88:89], v[88:89], v[90:91]
	v_mov_b32_e32 v90, v52
	v_mov_b32_e32 v91, v44
	v_cvt_pk_f16_f32 v46, v46, v47
	v_cvt_pk_f16_f32 v47, v48, v49
	v_pk_fma_f32 v[88:89], v[90:91], v[90:91], v[88:89]
	v_mov_b32_e32 v90, v53
	v_mov_b32_e32 v91, v45
	v_pk_mul_f32 v[54:55], v[54:55], v[0:1] op_sel_hi:[1,0]
	v_pk_mul_f32 v[56:57], v[56:57], v[0:1] op_sel_hi:[1,0]
	global_store_dwordx2 v[78:79], v[46:47], off offset:1024
	v_pk_mul_f32 v[46:47], v[58:59], v[0:1] op_sel_hi:[1,0]
	v_pk_mul_f32 v[48:49], v[60:61], v[0:1] op_sel_hi:[1,0]
	v_pk_fma_f32 v[80:81], v[90:91], v[90:91], v[88:89]
	v_cvt_pk_f16_f32 v54, v54, v55
	v_cvt_pk_f16_f32 v55, v56, v57
	v_cvt_pk_f16_f32 v46, v46, v47
	v_cvt_pk_f16_f32 v47, v48, v49
	v_mov_b32_e32 v48, v84
	v_mov_b32_e32 v49, v86
	v_mov_b32_e32 v86, v85
	global_store_dwordx2 v[78:79], v[54:55], off
	v_pk_add_f32 v[48:49], v[48:49], v[86:87]
	v_mov_b32_e32 v54, v80
	v_mov_b32_e32 v55, v82
	v_pk_add_f32 v[48:49], v[48:49], v[54:55]
	v_mov_b32_e32 v82, v81
	v_pk_add_f32 v[48:49], v[48:49], v[82:83]
	ds_bpermute_b32 v55, v163, v49
	ds_bpermute_b32 v54, v163, v48
	v_mul_f32_e32 v0, 0x4b800000, v68
	v_cmp_gt_f32_e32 vcc, s0, v68
	global_store_dwordx2 v[78:79], v[46:47], off offset:1536
	s_waitcnt lgkmcnt(0)
	v_pk_add_f32 v[48:49], v[48:49], v[54:55]
	ds_bpermute_b32 v55, v164, v49
	ds_bpermute_b32 v54, v164, v48
	v_cndmask_b32_e32 v0, v68, v0, vcc
	v_rsq_f32_e32 v0, v0
	s_waitcnt lgkmcnt(0)
	v_pk_add_f32 v[48:49], v[48:49], v[54:55]
	ds_bpermute_b32 v55, v165, v49
	ds_bpermute_b32 v54, v165, v48
	v_mul_f32_e32 v46, 0x45800000, v0
	v_cndmask_b32_e32 v0, v0, v46, vcc
	v_lshlrev_b64 v[46:47], 11, v[74:75]
	v_pk_mul_f32 v[26:27], v[26:27], v[0:1] op_sel_hi:[1,0]
	v_pk_mul_f32 v[28:29], v[28:29], v[0:1] op_sel_hi:[1,0]
	v_lshl_add_u64 v[46:47], v[66:67], 0, v[46:47]
	v_cvt_pk_f16_f32 v26, v26, v27
	v_cvt_pk_f16_f32 v27, v28, v29
	global_store_dwordx2 v[46:47], v[26:27], off
	s_waitcnt lgkmcnt(0)
; DI unsigned pk2(float lo, float hi) { f32x2 v = {lo, hi}; bf2_t b = __builtin_convertvector(v, bf2_t); return __builtin_bit_cast(unsigned, b); }
; template <int MODE, int MT> DI void norm_rows(const float* src, const float* src2, float* x, int d2, bf16_t* xb, const float* __restrict__ g) {
;     ...
; #pragma unroll
;         for (int q = 0; q < 4; ++q) {
;             const int row = wave * (MT * 4) + rb * 4 + q, grow = row + (row >= 64 ? d2 : 0);
;             const float rstd = rsqrtf(ss[q] * (1.f / DM) + 1e-6f);
; #pragma unroll
;             for (int i = 0; i < 4; ++i) {
;                 if (MODE == 0) *(f32x4*)(x + (size_t)grow * DM + i * 256 + lane * 4) = v[q][i];
;                 if (MODE == 2) { f32x4 gg = *(const f32x4*)(g + i * 256 + lane * 4); *(f32x4*)(x + (size_t)grow * DM + i * 256 + lane * 4) = v[q][i] * rstd * gg; }
;                 else { u32x2 o = {pk2(v[q][i][0] * rstd, v[q][i][1] * rstd), pk2(v[q][i][2] * rstd, v[q][i][3] * rstd)}; *(u32x2*)(xb + (size_t)grow * DM + i * 256 + lane * 4) = o; }
;             }
;         }
; template <int K, class Epi>
; DI void gemm64_res(const bf16_t* A, int lda, const bf16_t* Wp, int NU, unsigned char* lds, const Epi& epi) {
;     ...
;     __syncthreads();
; #pragma unroll
;     for (int i0 = 0; i0 < NIT; i0 += 8) {
;         u32x4 t8[8];
; #pragma unroll
;         for (int i = 0; i < 8; ++i) { const int idx = (i0 + i) * NTHR + tid, row = idx / SEGS, seg = idx % SEGS; t8[i] = *(const u32x4*)(A + (row * lda + seg * 8)); }
; #pragma unroll
;         for (int i = 0; i < 8; ++i) { const int idx = (i0 + i) * NTHR + tid, row = idx / SEGS, seg = idx % SEGS; *(u32x4*)(lds + row * LD + seg * 16) = t8[i]; }
	v_pk_add_f32 v[26:27], v[48:49], v[54:55]
	ds_bpermute_b32 v29, v166, v27
	ds_bpermute_b32 v28, v166, v26
	v_pk_mul_f32 v[2:3], v[2:3], v[0:1] op_sel_hi:[1,0]
	v_pk_mul_f32 v[4:5], v[4:5], v[0:1] op_sel_hi:[1,0]
	v_cvt_pk_f16_f32 v2, v2, v3
	v_cvt_pk_f16_f32 v3, v4, v5
	s_waitcnt lgkmcnt(0)
	v_pk_add_f32 v[4:5], v[26:27], v[28:29]
	global_store_dwordx2 v[46:47], v[2:3], off offset:512
	v_pk_mul_f32 v[2:3], v[22:23], v[0:1] op_sel_hi:[1,0]
	ds_bpermute_b32 v23, v167, v5
	ds_bpermute_b32 v22, v167, v4
	v_pk_mul_f32 v[24:25], v[24:25], v[0:1] op_sel_hi:[1,0]
	v_cvt_pk_f16_f32 v2, v2, v3
	v_cvt_pk_f16_f32 v3, v24, v25
	global_store_dwordx2 v[46:47], v[2:3], off offset:1024
	s_waitcnt lgkmcnt(0)
	v_pk_add_f32 v[2:3], v[4:5], v[22:23]
	ds_bpermute_b32 v5, v168, v3
	ds_bpermute_b32 v4, v168, v2
	v_pk_mul_f32 v[10:11], v[10:11], v[0:1] op_sel_hi:[1,0]
	v_pk_mul_f32 v[12:13], v[12:13], v[0:1] op_sel_hi:[1,0]
	v_cvt_pk_f16_f32 v10, v10, v11
	v_cvt_pk_f16_f32 v11, v12, v13
	s_waitcnt lgkmcnt(0)
	v_pk_add_f32 v[2:3], v[2:3], v[4:5]
	global_store_dwordx2 v[46:47], v[10:11], off offset:1536
	v_pk_fma_f32 v[2:3], v[2:3], s[2:3], v[70:71] op_sel_hi:[1,0,0]
	v_lshlrev_b64 v[4:5], 11, v[72:73]
	v_mul_f32_e32 v0, 0x4b800000, v3
	v_cmp_gt_f32_e32 vcc, s0, v3
	v_lshl_add_u64 v[4:5], v[66:67], 0, v[4:5]
	s_nop 0
	v_cndmask_b32_e32 v0, v3, v0, vcc
	v_rsq_f32_e32 v0, v0
	s_nop 0
	v_mul_f32_e32 v3, 0x45800000, v0
	v_cndmask_b32_e32 v0, v0, v3, vcc
	v_pk_mul_f32 v[10:11], v[18:19], v[0:1] op_sel_hi:[1,0]
	v_pk_mul_f32 v[12:13], v[20:21], v[0:1] op_sel_hi:[1,0]
	v_cvt_pk_f16_f32 v10, v10, v11
	v_cvt_pk_f16_f32 v11, v12, v13
	global_store_dwordx2 v[4:5], v[10:11], off
	v_pk_mul_f32 v[10:11], v[14:15], v[0:1] op_sel_hi:[1,0]
	v_pk_mul_f32 v[12:13], v[16:17], v[0:1] op_sel_hi:[1,0]
	v_cvt_pk_f16_f32 v10, v10, v11
	v_cvt_pk_f16_f32 v11, v12, v13
	global_store_dwordx2 v[4:5], v[10:11], off offset:512
	v_pk_mul_f32 v[10:11], v[30:31], v[0:1] op_sel_hi:[1,0]
	v_pk_mul_f32 v[12:13], v[32:33], v[0:1] op_sel_hi:[1,0]
	v_mul_f32_e32 v3, 0x4b800000, v2
	v_cmp_gt_f32_e32 vcc, s0, v2
	v_cvt_pk_f16_f32 v10, v10, v11
	v_cvt_pk_f16_f32 v11, v12, v13
	v_cndmask_b32_e32 v2, v2, v3, vcc
	global_store_dwordx2 v[4:5], v[10:11], off offset:1024
	v_rsq_f32_e32 v10, v2
	v_pk_mul_f32 v[6:7], v[6:7], v[0:1] op_sel_hi:[1,0]
	v_pk_mul_f32 v[2:3], v[8:9], v[0:1] op_sel_hi:[1,0]
	v_cvt_pk_f16_f32 v6, v6, v7
	v_mul_f32_e32 v0, 0x45800000, v10
	v_cvt_pk_f16_f32 v7, v2, v3
	v_cndmask_b32_e32 v0, v10, v0, vcc
	global_store_dwordx2 v[4:5], v[6:7], off offset:1536
	v_lshlrev_b64 v[2:3], 11, v[76:77]
	v_pk_mul_f32 v[4:5], v[38:39], v[0:1] op_sel_hi:[1,0]
	v_pk_mul_f32 v[6:7], v[40:41], v[0:1] op_sel_hi:[1,0]
	v_lshl_add_u64 v[2:3], v[66:67], 0, v[2:3]
	v_cvt_pk_f16_f32 v4, v4, v5
	v_cvt_pk_f16_f32 v5, v6, v7
	global_store_dwordx2 v[2:3], v[4:5], off
	v_pk_mul_f32 v[4:5], v[34:35], v[0:1] op_sel_hi:[1,0]
	v_pk_mul_f32 v[6:7], v[36:37], v[0:1] op_sel_hi:[1,0]
	v_cvt_pk_f16_f32 v4, v4, v5
	v_cvt_pk_f16_f32 v5, v6, v7
	global_store_dwordx2 v[2:3], v[4:5], off offset:512
	v_pk_mul_f32 v[4:5], v[50:51], v[0:1] op_sel_hi:[1,0]
	v_pk_mul_f32 v[6:7], v[52:53], v[0:1] op_sel_hi:[1,0]
	v_cvt_pk_f16_f32 v4, v4, v5
	v_cvt_pk_f16_f32 v5, v6, v7
	global_store_dwordx2 v[2:3], v[4:5], off offset:1024
	v_pk_mul_f32 v[4:5], v[42:43], v[0:1] op_sel_hi:[1,0]
	v_pk_mul_f32 v[6:7], v[44:45], v[0:1] op_sel_hi:[1,0]
	v_cvt_pk_f16_f32 v4, v4, v5
	v_cvt_pk_f16_f32 v5, v6, v7
	global_store_dwordx2 v[2:3], v[4:5], off offset:1536
	v_mov_b32_e32 v2, v176
	s_nop 0
	v_add_u32_e32 v0, 0x200, v2
	v_lshlrev_b32_e32 v4, 3, v2
	v_lshlrev_b32_e32 v6, 3, v0
	v_ashrrev_i32_e32 v5, 31, v4
	v_ashrrev_i32_e32 v7, 31, v6
	v_lshl_add_u64 v[4:5], v[4:5], 1, s[4:5]
	v_lshl_add_u64 v[8:9], v[6:7], 1, s[4:5]
	s_barrier
	global_load_dwordx4 v[4:7], v[4:5], off
	s_nop 0
	global_load_dwordx4 v[8:11], v[8:9], off
	v_add_u32_e32 v3, 0x400, v2
	v_add_u32_e32 v24, 0x600, v2
	v_lshlrev_b32_e32 v12, 3, v3
	v_lshlrev_b32_e32 v14, 3, v24
	v_ashrrev_i32_e32 v13, 31, v12
	v_ashrrev_i32_e32 v15, 31, v14
	v_lshl_add_u64 v[12:13], v[12:13], 1, s[4:5]
	v_lshl_add_u64 v[16:17], v[14:15], 1, s[4:5]
	v_add_u32_e32 v25, 0x800, v2
	global_load_dwordx4 v[12:15], v[12:13], off
	s_nop 0
	global_load_dwordx4 v[16:19], v[16:17], off
	v_lshlrev_b32_e32 v20, 3, v25
	v_ashrrev_i32_e32 v21, 31, v20
	v_lshl_add_u64 v[20:21], v[20:21], 1, s[4:5]
	global_load_dwordx4 v[20:23], v[20:21], off
	v_ashrrev_i32_e32 v26, 31, v2
	v_lshrrev_b32_e32 v26, 25, v26
	v_add_u32_e32 v26, v2, v26
	v_ashrrev_i32_e32 v36, 7, v26
	v_and_b32_e32 v26, 0xfffff80, v26
	v_sub_u32_e32 v37, v2, v26
	v_ashrrev_i32_e32 v26, 31, v0
	v_lshrrev_b32_e32 v26, 25, v26
	v_add_u32_e32 v26, v0, v26
	v_ashrrev_i32_e32 v38, 7, v26
	v_and_b32_e32 v26, 0xfffff80, v26
	v_sub_u32_e32 v0, v0, v26
	v_ashrrev_i32_e32 v26, 31, v3
	v_lshrrev_b32_e32 v26, 25, v26
	v_add_u32_e32 v26, v3, v26
	v_ashrrev_i32_e32 v39, 7, v26
	v_and_b32_e32 v26, 0xfffff80, v26
	v_sub_u32_e32 v3, v3, v26
	v_ashrrev_i32_e32 v26, 31, v24
	v_lshrrev_b32_e32 v26, 25, v26
	v_add_u32_e32 v26, v24, v26
	v_ashrrev_i32_e32 v40, 7, v26
	v_and_b32_e32 v26, 0xfffff80, v26
	v_sub_u32_e32 v41, v24, v26
	v_ashrrev_i32_e32 v24, 31, v25
	v_lshrrev_b32_e32 v24, 25, v24
	v_add_u32_e32 v24, v25, v24
	v_ashrrev_i32_e32 v42, 7, v24
	v_and_b32_e32 v24, 0xfffff80, v24
	v_add_u32_e32 v44, 0xa00, v2
	v_sub_u32_e32 v43, v25, v24
	v_ashrrev_i32_e32 v24, 31, v44
	v_lshrrev_b32_e32 v45, 25, v24
	v_lshlrev_b32_e32 v24, 3, v44
	v_ashrrev_i32_e32 v25, 31, v24
	v_add_u32_e32 v46, 0xc00, v2
	v_lshl_add_u64 v[24:25], v[24:25], 1, s[4:5]
	v_lshlrev_b32_e32 v28, 3, v46
	v_mul_lo_u32 v36, v36, s17
	global_load_dwordx4 v[24:27], v[24:25], off
	v_ashrrev_i32_e32 v29, 31, v28
	v_add_u32_e32 v47, 0xe00, v2
	v_lshl_add_u32 v36, v37, 4, v36
	v_lshl_add_u64 v[28:29], v[28:29], 1, s[4:5]
	v_lshlrev_b32_e32 v32, 3, v47
	global_load_dwordx4 v[28:31], v[28:29], off
	v_ashrrev_i32_e32 v33, 31, v32
	v_lshl_add_u64 v[32:33], v[32:33], 1, s[4:5]
	global_load_dwordx4 v[32:35], v[32:33], off
	v_add_u32_e32 v45, v44, v45
	v_ashrrev_i32_e32 v48, 7, v45
	v_add_u32_e32 v54, 0x1400, v2
	v_add_u32_e32 v55, 0x1600, v2
	v_and_b32_e32 v45, 0xfffff80, v45
	v_sub_u32_e32 v49, v44, v45
	v_ashrrev_i32_e32 v44, 31, v46
	v_lshrrev_b32_e32 v44, 25, v44
	v_add_u32_e32 v44, v46, v44
	v_add_u32_e32 v56, 0x1800, v2
	v_add_u32_e32 v57, 0x1a00, v2
	v_ashrrev_i32_e32 v50, 7, v44
	v_and_b32_e32 v44, 0xfffff80, v44
	v_sub_u32_e32 v51, v46, v44
	v_ashrrev_i32_e32 v44, 31, v47
	s_waitcnt vmcnt(7)
; template <int K, class Epi>
; DI void gemm64_res(const bf16_t* A, int lda, const bf16_t* Wp, int NU, unsigned char* lds, const Epi& epi) {
;     ...
;     for (int i0 = 0; i0 < NIT; i0 += 8) {
;         u32x4 t8[8];
; #pragma unroll
;         for (int i = 0; i < 8; ++i) { const int idx = (i0 + i) * NTHR + tid, row = idx / SEGS, seg = idx % SEGS; t8[i] = *(const u32x4*)(A + (row * lda + seg * 8)); }
; #pragma unroll
;         for (int i = 0; i < 8; ++i) { const int idx = (i0 + i) * NTHR + tid, row = idx / SEGS, seg = idx % SEGS; *(u32x4*)(lds + row * LD + seg * 16) = t8[i]; }
;     }
;     __syncthreads();
;     const unsigned char* ab = lds + r * LD + 16 * h;
; #pragma unroll 1
;     for (int unit = wave; unit < NU; unit += NWAVE) {
	ds_write_b128 v36, v[4:7]
	v_mul_lo_u32 v4, v38, s17
	v_lshl_add_u32 v0, v0, 4, v4
	s_waitcnt vmcnt(6)
	ds_write_b128 v0, v[8:11]
	v_mul_lo_u32 v0, v39, s17
	v_lshl_add_u32 v0, v3, 4, v0
	v_add_u32_e32 v3, 0x1000, v2
	v_lshlrev_b32_e32 v4, 3, v3
	v_ashrrev_i32_e32 v5, 31, v4
	v_lshl_add_u64 v[4:5], v[4:5], 1, s[4:5]
	s_waitcnt vmcnt(5)
	ds_write_b128 v0, v[12:15]
	v_mul_lo_u32 v0, v40, s17
	v_lshl_add_u32 v0, v41, 4, v0
	s_waitcnt vmcnt(4)
	ds_write_b128 v0, v[16:19]
	v_mul_lo_u32 v0, v42, s17
	v_lshl_add_u32 v0, v43, 4, v0
	s_waitcnt vmcnt(3)
	ds_write_b128 v0, v[20:23]
	v_mul_lo_u32 v0, v48, s17
	v_add_u32_e32 v48, 0x1200, v2
	v_lshlrev_b32_e32 v6, 3, v48
	v_ashrrev_i32_e32 v7, 31, v6
	v_lshl_add_u64 v[8:9], v[6:7], 1, s[4:5]
	global_load_dwordx4 v[4:7], v[4:5], off
	s_nop 0
	global_load_dwordx4 v[8:11], v[8:9], off
	v_lshlrev_b32_e32 v12, 3, v54
	v_lshlrev_b32_e32 v14, 3, v55
	v_ashrrev_i32_e32 v13, 31, v12
	v_ashrrev_i32_e32 v15, 31, v14
	v_lshl_add_u64 v[12:13], v[12:13], 1, s[4:5]
	v_lshl_add_u64 v[16:17], v[14:15], 1, s[4:5]
	global_load_dwordx4 v[12:15], v[12:13], off
	s_nop 0
	global_load_dwordx4 v[16:19], v[16:17], off
	v_lshlrev_b32_e32 v20, 3, v56
	v_lshlrev_b32_e32 v22, 3, v57
	v_ashrrev_i32_e32 v21, 31, v20
	v_ashrrev_i32_e32 v23, 31, v22
	v_lshrrev_b32_e32 v44, 25, v44
	v_lshl_add_u64 v[20:21], v[20:21], 1, s[4:5]
	v_lshl_add_u64 v[36:37], v[22:23], 1, s[4:5]
	v_add_u32_e32 v58, 0x1c00, v2
	v_add_u32_e32 v44, v47, v44
	global_load_dwordx4 v[20:23], v[20:21], off
	s_nop 0
	global_load_dwordx4 v[36:39], v[36:37], off
	v_lshlrev_b32_e32 v40, 3, v58
	v_ashrrev_i32_e32 v52, 7, v44
	v_and_b32_e32 v44, 0xfffff80, v44
	v_ashrrev_i32_e32 v41, 31, v40
	v_add_u32_e32 v59, 0x1e00, v2
	v_sub_u32_e32 v53, v47, v44
	v_lshl_add_u64 v[40:41], v[40:41], 1, s[4:5]
	v_lshlrev_b32_e32 v44, 3, v59
	global_load_dwordx4 v[40:43], v[40:41], off
	v_ashrrev_i32_e32 v45, 31, v44
	v_lshl_add_u64 v[44:45], v[44:45], 1, s[4:5]
	global_load_dwordx4 v[44:47], v[44:45], off
	v_lshl_add_u32 v0, v49, 4, v0
	v_readfirstlane_b32 s0, v2
	s_ashr_i32 s31, s0, 6
	s_waitcnt vmcnt(10)
	ds_write_b128 v0, v[24:27]
	v_mul_lo_u32 v0, v50, s17
	v_lshl_add_u32 v0, v51, 4, v0
	v_ashrrev_i32_e32 v26, 31, v54
	v_lshrrev_b32_e32 v26, 25, v26
	v_add_u32_e32 v26, v54, v26
	s_waitcnt vmcnt(9)
	ds_write_b128 v0, v[28:31]
	v_mul_lo_u32 v0, v52, s17
	v_lshl_add_u32 v0, v53, 4, v0
	s_waitcnt vmcnt(8)
	ds_write_b128 v0, v[32:35]
	v_ashrrev_i32_e32 v0, 31, v3
	v_lshrrev_b32_e32 v0, 25, v0
	v_add_u32_e32 v0, v3, v0
	v_ashrrev_i32_e32 v24, 7, v0
	v_and_b32_e32 v0, 0xfffff80, v0
	v_sub_u32_e32 v0, v3, v0
	v_ashrrev_i32_e32 v3, 31, v48
	v_lshrrev_b32_e32 v3, 25, v3
	v_add_u32_e32 v3, v48, v3
	v_mul_lo_u32 v24, v24, s17
	v_ashrrev_i32_e32 v25, 7, v3
	v_and_b32_e32 v3, 0xfffff80, v3
	v_lshl_add_u32 v0, v0, 4, v24
	v_sub_u32_e32 v3, v48, v3
	v_ashrrev_i32_e32 v28, 31, v55
	v_ashrrev_i32_e32 v27, 7, v26
	v_and_b32_e32 v26, 0xfffff80, v26
	v_lshrrev_b32_e32 v28, 25, v28
	v_sub_u32_e32 v26, v54, v26
	v_add_u32_e32 v28, v55, v28
	v_ashrrev_i32_e32 v30, 31, v56
	v_ashrrev_i32_e32 v29, 7, v28
	v_and_b32_e32 v28, 0xfffff80, v28
	v_lshrrev_b32_e32 v30, 25, v30
	v_sub_u32_e32 v28, v55, v28
	v_add_u32_e32 v30, v56, v30
	v_ashrrev_i32_e32 v32, 31, v57
	v_ashrrev_i32_e32 v31, 7, v30
	v_and_b32_e32 v30, 0xfffff80, v30
	v_lshrrev_b32_e32 v32, 25, v32
	v_sub_u32_e32 v30, v56, v30
	v_add_u32_e32 v32, v57, v32
	v_ashrrev_i32_e32 v34, 31, v58
	v_ashrrev_i32_e32 v33, 7, v32
	v_and_b32_e32 v32, 0xfffff80, v32
	v_lshrrev_b32_e32 v34, 25, v34
	s_waitcnt vmcnt(7)
	ds_write_b128 v0, v[4:7]
	v_mul_lo_u32 v0, v25, s17
	v_lshl_add_u32 v0, v3, 4, v0
	s_waitcnt vmcnt(6)
	ds_write_b128 v0, v[8:11]
	v_mul_lo_u32 v0, v27, s17
	v_lshl_add_u32 v0, v26, 4, v0
	v_sub_u32_e32 v32, v57, v32
	s_waitcnt vmcnt(5)
	ds_write_b128 v0, v[12:15]
	v_mul_lo_u32 v0, v29, s17
	v_lshl_add_u32 v0, v28, 4, v0
	s_waitcnt vmcnt(4)
	ds_write_b128 v0, v[16:19]
	v_mul_lo_u32 v0, v31, s17
	v_lshl_add_u32 v0, v30, 4, v0
	v_add_u32_e32 v34, v58, v34
	v_ashrrev_i32_e32 v48, 31, v59
	v_ashrrev_i32_e32 v35, 7, v34
	v_and_b32_e32 v34, 0xfffff80, v34
	s_waitcnt vmcnt(3)
	ds_write_b128 v0, v[20:23]
	v_mul_lo_u32 v0, v33, s17
	v_lshrrev_b32_e32 v48, 25, v48
	v_lshl_add_u32 v0, v32, 4, v0
	v_sub_u32_e32 v34, v58, v34
	v_add_u32_e32 v48, v59, v48
	s_waitcnt vmcnt(2)
	ds_write_b128 v0, v[36:39]
	v_mul_lo_u32 v0, v35, s17
	v_ashrrev_i32_e32 v49, 7, v48
	v_and_b32_e32 v48, 0xfffff80, v48
	v_lshl_add_u32 v0, v34, 4, v0
	v_sub_u32_e32 v48, v59, v48
	s_waitcnt vmcnt(1)
	ds_write_b128 v0, v[40:43]
	v_mul_lo_u32 v0, v49, s17
	v_lshl_add_u32 v0, v48, 4, v0
	s_cmpk_lt_i32 s31, 0x58
	s_waitcnt vmcnt(0)
	ds_write_b128 v0, v[44:47]
	s_waitcnt lgkmcnt(0)
	s_barrier
	s_cbranch_scc0 .LBB0_482
	v_readlane_b32 s0, v254, 57
	s_nop 3
	s_bitcmp1_b32 s0, 0
	s_cbranch_scc0 .Lep_skip
; DI int otid() { int t = threadIdx.x; asm volatile("" : "+v"(t)); return t; }
; DI const bf16_t* wp(const Params& p, int l, size_t off) { return (const bf16_t*)(p.ws + OFF_WP) + (size_t)l * PW_LAYER + off; }
; template <int MT> DI void phaseB(const Params& p, int l, int t, unsigned char* lds) {
;     ...
;     EpiUp<MT> eu; eu.priv = priv; eu.d2 = d2;
;     eu.halo = (float*)(ws + OFF_UHALO) + (size_t)t * 2 * DFF2;
;     eu.pconv = t == NTILE - 1 ? p.out + O_PCONV + (size_t)l * 2 * DFF2 : nullptr;
;     eu.sconv = p.out + O_SCONV + ((size_t)l * 8 + 2 * t) * 2 * DFF2;
;     gemm64<1024, MT>(xb, DM, d2, wp(p, l, PW_UP), DFF2 / UW, lds, eu);
; __global__ void __launch_bounds__(NTHR) mega(Params p) {
;     ...
;         if (l + 1 < DEPTH) {
;             if (G > 8) { if (tb >= 4) pack_layer(p, l + 1, (tb - 4) * NTHR + otid(), (G - 4) * NTHR); }
;             else pack_layer(p, l + 1, bid * NTHR + otid(), G * NTHR);
	v_writelane_b32 v246, s0, 0
	v_writelane_b32 v246, s1, 1
	v_writelane_b32 v246, s2, 2
	v_writelane_b32 v246, s3, 3
	v_writelane_b32 v246, s4, 4
	v_writelane_b32 v246, s5, 5
	v_writelane_b32 v246, s6, 6
	v_writelane_b32 v246, s7, 7
	v_writelane_b32 v246, s8, 8
	v_writelane_b32 v246, s9, 9
	v_writelane_b32 v246, s10, 10
	v_writelane_b32 v246, s11, 11
	v_writelane_b32 v246, s12, 12
	v_writelane_b32 v246, s13, 13
	v_writelane_b32 v246, s14, 14
	v_writelane_b32 v246, s15, 15
	v_writelane_b32 v246, s16, 16
	v_writelane_b32 v246, s17, 17
	v_writelane_b32 v246, s18, 18
	v_writelane_b32 v246, s19, 19
	v_writelane_b32 v246, s20, 20
	v_writelane_b32 v246, s21, 21
	v_writelane_b32 v246, s22, 22
	v_writelane_b32 v246, s23, 23
	v_writelane_b32 v246, s24, 24
	v_writelane_b32 v246, s25, 25
	v_writelane_b32 v246, s26, 26
	v_writelane_b32 v246, s27, 27
	v_writelane_b32 v246, s28, 28
	v_writelane_b32 v246, s29, 29
	v_writelane_b32 v246, s30, 30
	v_writelane_b32 v246, s31, 31
	v_writelane_b32 v246, s32, 32
	v_writelane_b32 v246, s33, 33
	v_writelane_b32 v246, s34, 34
	v_writelane_b32 v246, s35, 35
	v_writelane_b32 v246, s36, 36
	v_writelane_b32 v246, s37, 37
	v_writelane_b32 v246, s38, 38
	v_writelane_b32 v246, s39, 39
	v_writelane_b32 v246, s40, 40
	v_writelane_b32 v246, s41, 41
	v_writelane_b32 v246, s42, 42
	v_writelane_b32 v246, s43, 43
	v_writelane_b32 v246, s44, 44
	v_writelane_b32 v246, s45, 45
	v_writelane_b32 v246, s46, 46
	v_writelane_b32 v246, s47, 47
	v_writelane_b32 v246, s48, 48
	v_writelane_b32 v246, s49, 49
	v_writelane_b32 v246, s50, 50
	v_writelane_b32 v246, s51, 51
	v_writelane_b32 v246, s52, 52
	v_writelane_b32 v246, s53, 53
	v_writelane_b32 v246, s54, 54
	v_writelane_b32 v246, s55, 55
	v_writelane_b32 v246, s56, 56
	v_writelane_b32 v246, s57, 57
	v_writelane_b32 v246, s58, 58
	v_writelane_b32 v246, s59, 59
	v_writelane_b32 v246, s60, 60
	v_writelane_b32 v246, s61, 61
	v_writelane_b32 v246, s62, 62
	v_writelane_b32 v246, s63, 63
	v_writelane_b32 v247, s64, 0
	v_writelane_b32 v247, s65, 1
	v_writelane_b32 v247, s66, 2
	v_writelane_b32 v247, s67, 3
	v_writelane_b32 v247, s68, 4
	v_writelane_b32 v247, s69, 5
	v_writelane_b32 v247, s70, 6
	v_writelane_b32 v247, s71, 7
	v_writelane_b32 v247, s72, 8
	v_writelane_b32 v247, s73, 9
	v_writelane_b32 v247, s74, 10
	v_writelane_b32 v247, s75, 11
	v_writelane_b32 v247, s76, 12
	v_writelane_b32 v247, s77, 13
	v_writelane_b32 v247, s78, 14
	v_writelane_b32 v247, s79, 15
	v_writelane_b32 v247, s80, 16
	v_writelane_b32 v247, s81, 17
	v_writelane_b32 v247, s82, 18
	v_writelane_b32 v247, s83, 19
	v_writelane_b32 v247, s84, 20
	v_writelane_b32 v247, s85, 21
	v_writelane_b32 v247, s86, 22
	v_writelane_b32 v247, s87, 23
	v_writelane_b32 v247, s88, 24
	v_writelane_b32 v247, s89, 25
	v_writelane_b32 v247, s90, 26
	v_writelane_b32 v247, s91, 27
	v_writelane_b32 v247, s92, 28
	v_writelane_b32 v247, s93, 29
	v_writelane_b32 v247, s94, 30
	v_writelane_b32 v247, s95, 31
	v_writelane_b32 v247, s96, 32
	v_writelane_b32 v247, s97, 33
	v_writelane_b32 v247, s98, 34
	v_writelane_b32 v247, s99, 35
	v_writelane_b32 v247, s100, 36
	v_writelane_b32 v247, s101, 37
	v_writelane_b32 v247, vcc_lo, 38
	v_writelane_b32 v247, vcc_hi, 39
	v_mov_b32_e32 v248, v2
	s_mov_b32 s0, 0x5ac0
	s_nop 1
	v_writelane_b32 v255, s0, 57
	s_branch .LBB0_554
.Lep_back:
	v_readlane_b32 s0, v246, 0
	v_readlane_b32 s1, v246, 1
	v_readlane_b32 s2, v246, 2
	v_readlane_b32 s3, v246, 3
	v_readlane_b32 s4, v246, 4
	v_readlane_b32 s5, v246, 5
	v_readlane_b32 s6, v246, 6
	v_readlane_b32 s7, v246, 7
	v_readlane_b32 s8, v246, 8
	v_readlane_b32 s9, v246, 9
	v_readlane_b32 s10, v246, 10
	v_readlane_b32 s11, v246, 11
	v_readlane_b32 s12, v246, 12
	v_readlane_b32 s13, v246, 13
	v_readlane_b32 s14, v246, 14
	v_readlane_b32 s15, v246, 15
	v_readlane_b32 s16, v246, 16
	v_readlane_b32 s17, v246, 17
	v_readlane_b32 s18, v246, 18
	v_readlane_b32 s19, v246, 19
	v_readlane_b32 s20, v246, 20
	v_readlane_b32 s21, v246, 21
	v_readlane_b32 s22, v246, 22
	v_readlane_b32 s23, v246, 23
	v_readlane_b32 s24, v246, 24
	v_readlane_b32 s25, v246, 25
	v_readlane_b32 s26, v246, 26
	v_readlane_b32 s27, v246, 27
	v_readlane_b32 s28, v246, 28
	v_readlane_b32 s29, v246, 29
	v_readlane_b32 s30, v246, 30
	v_readlane_b32 s31, v246, 31
	v_readlane_b32 s32, v246, 32
	v_readlane_b32 s33, v246, 33
	v_readlane_b32 s34, v246, 34
	v_readlane_b32 s35, v246, 35
	v_readlane_b32 s36, v246, 36
	v_readlane_b32 s37, v246, 37
	v_readlane_b32 s38, v246, 38
	v_readlane_b32 s39, v246, 39
	v_readlane_b32 s40, v246, 40
	v_readlane_b32 s41, v246, 41
	v_readlane_b32 s42, v246, 42
	v_readlane_b32 s43, v246, 43
	v_readlane_b32 s44, v246, 44
	v_readlane_b32 s45, v246, 45
	v_readlane_b32 s46, v246, 46
	v_readlane_b32 s47, v246, 47
	v_readlane_b32 s48, v246, 48
	v_readlane_b32 s49, v246, 49
	v_readlane_b32 s50, v246, 50
	v_readlane_b32 s51, v246, 51
	v_readlane_b32 s52, v246, 52
	v_readlane_b32 s53, v246, 53
	v_readlane_b32 s54, v246, 54
	v_readlane_b32 s55, v246, 55
	v_readlane_b32 s56, v246, 56
	v_readlane_b32 s57, v246, 57
	v_readlane_b32 s58, v246, 58
	v_readlane_b32 s59, v246, 59
	v_readlane_b32 s60, v246, 60
	v_readlane_b32 s61, v246, 61
	v_readlane_b32 s62, v246, 62
	v_readlane_b32 s63, v246, 63
	v_readlane_b32 s64, v247, 0
	v_readlane_b32 s65, v247, 1
	v_readlane_b32 s66, v247, 2
	v_readlane_b32 s67, v247, 3
	v_readlane_b32 s68, v247, 4
	v_readlane_b32 s69, v247, 5
	v_readlane_b32 s70, v247, 6
	v_readlane_b32 s71, v247, 7
	v_readlane_b32 s72, v247, 8
	v_readlane_b32 s73, v247, 9
	v_readlane_b32 s74, v247, 10
	v_readlane_b32 s75, v247, 11
	v_readlane_b32 s76, v247, 12
	v_readlane_b32 s77, v247, 13
	v_readlane_b32 s78, v247, 14
	v_readlane_b32 s79, v247, 15
	v_readlane_b32 s80, v247, 16
	v_readlane_b32 s81, v247, 17
	v_readlane_b32 s82, v247, 18
	v_readlane_b32 s83, v247, 19
	v_readlane_b32 s84, v247, 20
	v_readlane_b32 s85, v247, 21
	v_readlane_b32 s86, v247, 22
	v_readlane_b32 s87, v247, 23
	v_readlane_b32 s88, v247, 24
	v_readlane_b32 s89, v247, 25
	v_readlane_b32 s90, v247, 26
	v_readlane_b32 s91, v247, 27
	v_readlane_b32 s92, v247, 28
	v_readlane_b32 s93, v247, 29
	v_readlane_b32 s94, v247, 30
	v_readlane_b32 s95, v247, 31
	v_readlane_b32 s96, v247, 32
	v_readlane_b32 s97, v247, 33
	v_readlane_b32 s98, v247, 34
	v_readlane_b32 s99, v247, 35
	v_readlane_b32 s100, v247, 36
	v_readlane_b32 s101, v247, 37
	v_readlane_b32 vcc_lo, v247, 38
	v_readlane_b32 vcc_hi, v247, 39
	v_mov_b32_e32 v2, v248
.Lep_skip:
	s_mul_i32 s64, s11, 0x2c00
	s_lshl_b64 s[0:1], s[64:65], 2
	v_readlane_b32 s2, v252, 45
	s_add_u32 s8, s2, s0
	v_readlane_b32 s0, v252, 46
	v_lshrrev_b32_e32 v3, 1, v2
	s_movk_i32 s3, 0x810
	s_addc_u32 s9, s0, s1
	v_and_b32_e32 v0, 31, v2
	v_and_b32_e32 v3, 16, v3
	v_and_b32_e32 v2, 63, v2
	v_readlane_b32 s0, v255, 44
	s_cmpk_eq_i32 s11, 0xff
	v_mad_u32_u24 v0, v0, s3, v3
	v_lshlrev_b32_e32 v2, 4, v2
	v_mov_b32_e32 v3, v1
	v_readlane_b32 s1, v255, 45
	s_cselect_b64 s[28:29], -1, 0
	v_add_u32_e32 v72, 0x10200, v0
	v_lshl_add_u64 v[66:67], s[0:1], 0, v[2:3]
	s_branch .LBB0_540

; DI int otid() { int t = threadIdx.x; asm volatile("" : "+v"(t)); return t; }
; __global__ void __launch_bounds__(NTHR) mega(Params p) {
;     ...
;         if (l + 1 < DEPTH) {
;             if (G > 8) { if (tb >= 4) pack_layer(p, l + 1, (tb - 4) * NTHR + otid(), (G - 4) * NTHR); }
;             else pack_layer(p, l + 1, bid * NTHR + otid(), G * NTHR);
;         }
.LBB0_555:
	s_add_i32 s90, s60, 1
	s_cmp_lg_u32 s60, 3
	s_cselect_b64 s[0:1], -1, 0
	v_writelane_b32 v255, s0, 49
	s_and_b64 vcc, exec, s[0:1]
	s_nop 0
	v_writelane_b32 v255, s1, 50
	s_cbranch_vccz .LBB0_705
	v_readlane_b32 s0, v255, 57
	s_nop 3
	s_cmp_eq_u32 s0, 0x5ac1
	s_cbranch_scc0 .Lep_dopack
	s_mov_b32 s0, 0
	s_nop 1
	v_writelane_b32 v255, s0, 57
	s_branch .LBB0_705
.Lep_dopack:
	v_readlane_b32 s2, v253, 41
	v_readlane_b32 s3, v253, 42
	s_mov_b64 s[0:1], -1
	s_and_b64 vcc, exec, s[2:3]
	s_cbranch_vccz .LBB0_630
	v_readlane_b32 s4, v252, 0
	v_mov_b32_e32 v0, v176
	v_readlane_b32 s0, v252, 12
	s_mul_i32 s1, s90, 0x1f00000
	v_readlane_b32 s8, v252, 4
	v_readlane_b32 s9, v252, 5
	v_add_u32_e32 v41, s0, v0
	s_mul_hi_u32 s0, s90, 0x1f00000
	s_add_u32 s52, s8, s1
	s_addc_u32 s53, s9, s0
	s_mov_b32 s0, 0x22000
	s_movk_i32 s31, 0x3fff
	s_mov_b32 s91, s65
	s_lshl_b32 s64, s90, 10
	v_cmp_gt_i32_e32 vcc, s0, v41
	v_lshlrev_b32_e32 v43, 2, v41
	v_readlane_b32 s5, v252, 1
	v_readlane_b32 s6, v252, 2
	v_readlane_b32 s7, v252, 3
	v_readlane_b32 s10, v252, 6
	v_readlane_b32 s11, v252, 7
	s_and_saveexec_b64 s[2:3], vcc
	s_cbranch_execz .LBB0_576
	v_readlane_b32 s4, v252, 55
	s_mul_i32 s1, s90, 0x1100000
	v_readlane_b32 s10, v252, 61
	s_mul_hi_u32 s0, s90, 0x1100000
	v_readlane_b32 s5, v252, 56
	v_readlane_b32 s11, v252, 62
	s_add_u32 s4, s10, s1
	v_readlane_b32 s6, v252, 57
	v_readlane_b32 s8, v252, 59
	s_addc_u32 s5, s11, s0
	s_lshl_b64 s[0:1], s[64:65], 2
	v_readlane_b32 s7, v252, 58
	v_readlane_b32 s9, v252, 60
	s_add_u32 s6, s8, s0
	s_addc_u32 s7, s9, s1
	v_lshlrev_b32_e32 v0, 2, v41
	s_mov_b64 s[10:11], 0
	v_mov_b32_e32 v40, v41
	v_readlane_b32 s12, v252, 63
	v_readlane_b32 s13, v253, 0
	v_readlane_b32 s14, v253, 1
	v_readlane_b32 s15, v253, 2
	v_readlane_b32 s16, v253, 3
	v_readlane_b32 s17, v253, 4
	v_readlane_b32 s18, v253, 5
	v_readlane_b32 s19, v253, 6
	s_branch .LBB0_560

; DI int otid() { int t = threadIdx.x; asm volatile("" : "+v"(t)); return t; }
; __global__ void __launch_bounds__(NTHR) mega(Params p) {
;     ...
;         if (l + 1 < DEPTH) {
;             if (G > 8) { if (tb >= 4) pack_layer(p, l + 1, (tb - 4) * NTHR + otid(), (G - 4) * NTHR); }
;             else pack_layer(p, l + 1, bid * NTHR + otid(), G * NTHR);
;         }
.LBB0_705:
	v_readlane_b32 s0, v255, 57
	s_nop 3
	s_cmp_eq_u32 s0, 0x5ac0
	s_cbranch_scc0 .Lep_not_a
	s_mov_b32 s0, 0x5ac1
	s_nop 1
	v_writelane_b32 v255, s0, 57
	s_branch .Lep_back
.Lep_not_a:
	s_cmp_eq_u32 s0, 0x5ac1
	s_cbranch_scc0 .Lep_cont
	s_mov_b32 s0, 0
	s_nop 1
	v_writelane_b32 v255, s0, 57
